# T21 store widening on the RoPE-tile GEMM epilogue: v_permlane16_swap_b32 between 16-lane rows, 32x dwordx2 -> 16x dwordx4 stores per wave per tile
# speedup vs baseline: 1.0169x; 1.0058x over previous
; __device__ __forceinline__ unsigned pk_bf16(float lo, float hi) { const f32x2 v = {lo, hi}; const bf16v2 b = __builtin_convertvector(v, bf16v2); return __builtin_bit_cast(unsigned, b); }
; template <class Epi>
; __device__ __forceinline__ void gemm_phase(const bf16_t* __restrict__ A, const bf16_t* __restrict__ Bt, int M, int N, LAS unsigned char* lds, const Epi& epi, int vcu) {
;     ...
;         for (int ai = 0; ai < 2; ++ai)
; #pragma unroll
;             for (int mp = 0; mp < 2; ++mp) {
; #pragma unroll
;                 for (int mq = 0; mq < 2; ++mq)
; #pragma unroll
;                     for (int bj = 0; bj < 2; ++bj) { const int m = mp * 2 + mq;
;                         epi(brow + ai * HALF + wr * 64 + m * 16 + fre, (bcol + bj * HALF + wc * 32) >> 5, fqe, acc[ai][bj][m][0], acc[ai][bj][m][1]); }
;     __device__ __forceinline__ void operator()(int row, int G, int fq, f32x4 v0, f32x4 v1) const {
;         const int col32 = G * 32;
;         const unsigned ro = (unsigned)row * (unsigned)ld;
;         if (col32 < rope_end) {
;             const int half = hd >> 1, hb = col32 & ~(hd - 1), d0 = ((col32 & (hd - 1)) >> 5) * 16 + fq * 4, pos = row & (SEQ - 1);
;             const unsigned to = (unsigned)(pos * half + d0);
;             const f32x4 c = *(const f32x4*)(cosT + to), s = *(const f32x4*)(sinT + to);
;             const f32x4 o1 = v0 * c - v1 * s, o2 = v1 * c + v0 * s;
;             u32x2 w1, w2; w1.x = pk_bf16(o1[0], o1[1]); w1.y = pk_bf16(o1[2], o1[3]); w2.x = pk_bf16(o2[0], o2[1]); w2.y = pk_bf16(o2[2], o2[3]);
;             *(u32x2*)(out + (ro + (unsigned)(hb + d0))) = w1; *(u32x2*)(out + (ro + (unsigned)(hb + half + d0))) = w2;
.Lre_entry:
	s_add_i32 s56, s44, s66
	s_and_b32 s2, s56, s28
	s_lshr_b32 s2, s2, 1
	s_and_b32 s10, s56, s37
	s_add_i32 s10, s10, s2
	s_add_i32 s11, s42, s65
	v_add_u32_e32 v149, s11, v139
	v_lshlrev_b32_e32 v212, 2, v140
	v_and_b32_e32 v213, 0x1fff, v149
	v_add_u32_e32 v214, s2, v212
	v_mad_u32_u24 v213, v213, s67, v214
	v_lshlrev_b32_e32 v213, 2, v213
	v_mul_lo_u32 v215, v149, s79
	v_add3_u32 v215, v215, s10, v212
	v_lshlrev_b32_e32 v215, 1, v215
	v_lshl_add_u32 v212, s67, 1, v215
	s_lshl_b32 s2, s67, 6
	s_mul_i32 s56, s2, 5
	s_lshl_b32 s10, s79, 5
	s_mul_i32 s11, s10, 5
	s_mov_b64 s[52:53], s[46:47]
	s_mov_b64 s[54:55], s[26:27]
	s_mov_b64 s[42:43], s[76:77]
	v_and_b32_e32 v214, 1, v140
	v_cmp_ne_u32_e32 vcc, 0, v214
	v_add_u32_e32 v214, -8, v212
	v_cndmask_b32_e32 v214, v215, v214, vcc
	global_load_dwordx4 v[150:153], v213, s[52:53]
	global_load_dwordx4 v[154:157], v213, s[54:55]
	s_add_u32 s52, s52, s2
	s_addc_u32 s53, s53, 0
	s_add_u32 s54, s54, s2
	s_addc_u32 s55, s55, 0
	global_load_dwordx4 v[158:161], v213, s[52:53]
	global_load_dwordx4 v[162:165], v213, s[54:55]
	s_add_u32 s52, s52, s2
	s_addc_u32 s53, s53, 0
	s_add_u32 s54, s54, s2
	s_addc_u32 s55, s55, 0
	global_load_dwordx4 v[166:169], v213, s[52:53]
	global_load_dwordx4 v[170:173], v213, s[54:55]
	s_add_u32 s52, s52, s2
	s_addc_u32 s53, s53, 0
	s_add_u32 s54, s54, s2
	s_addc_u32 s55, s55, 0
	global_load_dwordx4 v[174:177], v213, s[52:53]
	global_load_dwordx4 v[178:181], v213, s[54:55]
	s_add_u32 s52, s52, s56
	s_addc_u32 s53, s53, 0
	s_add_u32 s54, s54, s56
	s_addc_u32 s55, s55, 0
	global_load_dwordx4 v[182:185], v213, s[52:53]
	global_load_dwordx4 v[186:189], v213, s[54:55]
	s_add_u32 s52, s52, s2
	s_addc_u32 s53, s53, 0
	s_add_u32 s54, s54, s2
	s_addc_u32 s55, s55, 0
	global_load_dwordx4 v[190:193], v213, s[52:53]
	global_load_dwordx4 v[194:197], v213, s[54:55]
	s_add_u32 s52, s52, s2
	s_addc_u32 s53, s53, 0
	s_add_u32 s54, s54, s2
	s_addc_u32 s55, s55, 0
	s_waitcnt vmcnt(10)
	v_pk_mul_f32 v[218:219], v[122:123], v[154:155]
	v_pk_mul_f32 v[216:217], v[126:127], v[154:155]
	v_pk_fma_f32 v[122:123], v[122:123], v[150:151], v[216:217]
	v_pk_fma_f32 v[126:127], v[126:127], v[150:151], v[218:219] neg_lo:[0,0,1] neg_hi:[0,0,1]
	v_pk_mul_f32 v[218:219], v[124:125], v[156:157]
	v_pk_mul_f32 v[216:217], v[128:129], v[156:157]
	v_pk_fma_f32 v[124:125], v[124:125], v[152:153], v[216:217]
	v_pk_fma_f32 v[128:129], v[128:129], v[152:153], v[218:219] neg_lo:[0,0,1] neg_hi:[0,0,1]
	v_cvt_pk_bf16_f32 v126, v126, v127
	v_cvt_pk_bf16_f32 v127, v128, v129
	v_cvt_pk_bf16_f32 v128, v122, v123
	v_cvt_pk_bf16_f32 v129, v124, v125
	s_nop 1
	v_permlane16_swap_b32_e32 v126, v128
	v_permlane16_swap_b32_e32 v127, v129
	global_store_dwordx4 v214, v[126:129], s[42:43]
	v_pk_mul_f32 v[218:219], v[114:115], v[154:155]
	v_pk_mul_f32 v[216:217], v[118:119], v[154:155]
	v_pk_fma_f32 v[114:115], v[114:115], v[150:151], v[216:217]
	v_pk_fma_f32 v[118:119], v[118:119], v[150:151], v[218:219] neg_lo:[0,0,1] neg_hi:[0,0,1]
	v_pk_mul_f32 v[218:219], v[116:117], v[156:157]
	v_pk_mul_f32 v[216:217], v[120:121], v[156:157]
	v_pk_fma_f32 v[116:117], v[116:117], v[152:153], v[216:217]
	v_pk_fma_f32 v[120:121], v[120:121], v[152:153], v[218:219] neg_lo:[0,0,1] neg_hi:[0,0,1]
	v_cvt_pk_bf16_f32 v118, v118, v119
	v_cvt_pk_bf16_f32 v119, v120, v121
	v_cvt_pk_bf16_f32 v120, v114, v115
	v_cvt_pk_bf16_f32 v121, v116, v117
	s_nop 1
	v_permlane16_swap_b32_e32 v118, v120
	v_permlane16_swap_b32_e32 v119, v121
	global_store_dwordx4 v214, v[118:121], s[42:43] offset:256
	s_add_u32 s42, s42, s10
	s_addc_u32 s43, s43, 0
	s_waitcnt vmcnt(10)
	v_pk_mul_f32 v[218:219], v[106:107], v[162:163]
	v_pk_mul_f32 v[216:217], v[110:111], v[162:163]
	v_pk_fma_f32 v[106:107], v[106:107], v[158:159], v[216:217]
	v_pk_fma_f32 v[110:111], v[110:111], v[158:159], v[218:219] neg_lo:[0,0,1] neg_hi:[0,0,1]
	v_pk_mul_f32 v[218:219], v[108:109], v[164:165]
	v_pk_mul_f32 v[216:217], v[112:113], v[164:165]
	v_pk_fma_f32 v[108:109], v[108:109], v[160:161], v[216:217]
	v_pk_fma_f32 v[112:113], v[112:113], v[160:161], v[218:219] neg_lo:[0,0,1] neg_hi:[0,0,1]
	v_cvt_pk_bf16_f32 v110, v110, v111
	v_cvt_pk_bf16_f32 v111, v112, v113
	v_cvt_pk_bf16_f32 v112, v106, v107
	v_cvt_pk_bf16_f32 v113, v108, v109
	s_nop 1
	v_permlane16_swap_b32_e32 v110, v112
	v_permlane16_swap_b32_e32 v111, v113
	global_store_dwordx4 v214, v[110:113], s[42:43]
	v_pk_mul_f32 v[218:219], v[98:99], v[162:163]
	v_pk_mul_f32 v[216:217], v[102:103], v[162:163]
	v_pk_fma_f32 v[98:99], v[98:99], v[158:159], v[216:217]
	v_pk_fma_f32 v[102:103], v[102:103], v[158:159], v[218:219] neg_lo:[0,0,1] neg_hi:[0,0,1]
	v_pk_mul_f32 v[218:219], v[100:101], v[164:165]
	v_pk_mul_f32 v[216:217], v[104:105], v[164:165]
	v_pk_fma_f32 v[100:101], v[100:101], v[160:161], v[216:217]
	v_pk_fma_f32 v[104:105], v[104:105], v[160:161], v[218:219] neg_lo:[0,0,1] neg_hi:[0,0,1]
	v_cvt_pk_bf16_f32 v102, v102, v103
	v_cvt_pk_bf16_f32 v103, v104, v105
	v_cvt_pk_bf16_f32 v104, v98, v99
	v_cvt_pk_bf16_f32 v105, v100, v101
	s_nop 1
	v_permlane16_swap_b32_e32 v102, v104
	v_permlane16_swap_b32_e32 v103, v105
	global_store_dwordx4 v214, v[102:105], s[42:43] offset:256
	s_add_u32 s42, s42, s10
	s_addc_u32 s43, s43, 0
	global_load_dwordx4 v[150:153], v213, s[52:53]
	global_load_dwordx4 v[154:157], v213, s[54:55]
	s_add_u32 s52, s52, s2
	s_addc_u32 s53, s53, 0
	s_add_u32 s54, s54, s2
	s_addc_u32 s55, s55, 0
	global_load_dwordx4 v[158:161], v213, s[52:53]
	global_load_dwordx4 v[162:165], v213, s[54:55]
	s_waitcnt vmcnt(14)
; __device__ __forceinline__ unsigned pk_bf16(float lo, float hi) { const f32x2 v = {lo, hi}; const bf16v2 b = __builtin_convertvector(v, bf16v2); return __builtin_bit_cast(unsigned, b); }
; template <class Epi>
; __device__ __forceinline__ void gemm_phase(const bf16_t* __restrict__ A, const bf16_t* __restrict__ Bt, int M, int N, LAS unsigned char* lds, const Epi& epi, int vcu) {
;     ...
;         for (int ai = 0; ai < 2; ++ai)
; #pragma unroll
;             for (int mp = 0; mp < 2; ++mp) {
; #pragma unroll
;                 for (int mq = 0; mq < 2; ++mq)
; #pragma unroll
;                     for (int bj = 0; bj < 2; ++bj) { const int m = mp * 2 + mq;
;                         epi(brow + ai * HALF + wr * 64 + m * 16 + fre, (bcol + bj * HALF + wc * 32) >> 5, fqe, acc[ai][bj][m][0], acc[ai][bj][m][1]); }
;     __device__ __forceinline__ void operator()(int row, int G, int fq, f32x4 v0, f32x4 v1) const {
;         const int col32 = G * 32;
;         const unsigned ro = (unsigned)row * (unsigned)ld;
;         if (col32 < rope_end) {
;             const int half = hd >> 1, hb = col32 & ~(hd - 1), d0 = ((col32 & (hd - 1)) >> 5) * 16 + fq * 4, pos = row & (SEQ - 1);
;             const unsigned to = (unsigned)(pos * half + d0);
;             const f32x4 c = *(const f32x4*)(cosT + to), s = *(const f32x4*)(sinT + to);
;             const f32x4 o1 = v0 * c - v1 * s, o2 = v1 * c + v0 * s;
;             u32x2 w1, w2; w1.x = pk_bf16(o1[0], o1[1]); w1.y = pk_bf16(o1[2], o1[3]); w2.x = pk_bf16(o2[0], o2[1]); w2.y = pk_bf16(o2[2], o2[3]);
;             *(u32x2*)(out + (ro + (unsigned)(hb + d0))) = w1; *(u32x2*)(out + (ro + (unsigned)(hb + half + d0))) = w2;
	v_pk_mul_f32 v[218:219], v[90:91], v[170:171]
	v_pk_mul_f32 v[216:217], v[94:95], v[170:171]
	v_pk_fma_f32 v[90:91], v[90:91], v[166:167], v[216:217]
	v_pk_fma_f32 v[94:95], v[94:95], v[166:167], v[218:219] neg_lo:[0,0,1] neg_hi:[0,0,1]
	v_pk_mul_f32 v[218:219], v[92:93], v[172:173]
	v_pk_mul_f32 v[216:217], v[96:97], v[172:173]
	v_pk_fma_f32 v[92:93], v[92:93], v[168:169], v[216:217]
	v_pk_fma_f32 v[96:97], v[96:97], v[168:169], v[218:219] neg_lo:[0,0,1] neg_hi:[0,0,1]
	v_cvt_pk_bf16_f32 v94, v94, v95
	v_cvt_pk_bf16_f32 v95, v96, v97
	v_cvt_pk_bf16_f32 v96, v90, v91
	v_cvt_pk_bf16_f32 v97, v92, v93
	s_nop 1
	v_permlane16_swap_b32_e32 v94, v96
	v_permlane16_swap_b32_e32 v95, v97
	global_store_dwordx4 v214, v[94:97], s[42:43]
	v_pk_mul_f32 v[218:219], v[82:83], v[170:171]
	v_pk_mul_f32 v[216:217], v[86:87], v[170:171]
	v_pk_fma_f32 v[82:83], v[82:83], v[166:167], v[216:217]
	v_pk_fma_f32 v[86:87], v[86:87], v[166:167], v[218:219] neg_lo:[0,0,1] neg_hi:[0,0,1]
	v_pk_mul_f32 v[218:219], v[84:85], v[172:173]
	v_pk_mul_f32 v[216:217], v[88:89], v[172:173]
	v_pk_fma_f32 v[84:85], v[84:85], v[168:169], v[216:217]
	v_pk_fma_f32 v[88:89], v[88:89], v[168:169], v[218:219] neg_lo:[0,0,1] neg_hi:[0,0,1]
	v_cvt_pk_bf16_f32 v86, v86, v87
	v_cvt_pk_bf16_f32 v87, v88, v89
	v_cvt_pk_bf16_f32 v88, v82, v83
	v_cvt_pk_bf16_f32 v89, v84, v85
	s_nop 1
	v_permlane16_swap_b32_e32 v86, v88
	v_permlane16_swap_b32_e32 v87, v89
	global_store_dwordx4 v214, v[86:89], s[42:43] offset:256
	s_add_u32 s42, s42, s10
	s_addc_u32 s43, s43, 0
	s_waitcnt vmcnt(14)
	v_pk_mul_f32 v[218:219], v[74:75], v[178:179]
	v_pk_mul_f32 v[216:217], v[78:79], v[178:179]
	v_pk_fma_f32 v[74:75], v[74:75], v[174:175], v[216:217]
	v_pk_fma_f32 v[78:79], v[78:79], v[174:175], v[218:219] neg_lo:[0,0,1] neg_hi:[0,0,1]
	v_pk_mul_f32 v[218:219], v[76:77], v[180:181]
	v_pk_mul_f32 v[216:217], v[80:81], v[180:181]
	v_pk_fma_f32 v[76:77], v[76:77], v[176:177], v[216:217]
	v_pk_fma_f32 v[80:81], v[80:81], v[176:177], v[218:219] neg_lo:[0,0,1] neg_hi:[0,0,1]
	v_cvt_pk_bf16_f32 v78, v78, v79
	v_cvt_pk_bf16_f32 v79, v80, v81
	v_cvt_pk_bf16_f32 v80, v74, v75
	v_cvt_pk_bf16_f32 v81, v76, v77
	s_nop 1
	v_permlane16_swap_b32_e32 v78, v80
	v_permlane16_swap_b32_e32 v79, v81
	global_store_dwordx4 v214, v[78:81], s[42:43]
	v_pk_mul_f32 v[218:219], v[66:67], v[178:179]
	v_pk_mul_f32 v[216:217], v[70:71], v[178:179]
	v_pk_fma_f32 v[66:67], v[66:67], v[174:175], v[216:217]
	v_pk_fma_f32 v[70:71], v[70:71], v[174:175], v[218:219] neg_lo:[0,0,1] neg_hi:[0,0,1]
	v_pk_mul_f32 v[218:219], v[68:69], v[180:181]
	v_pk_mul_f32 v[216:217], v[72:73], v[180:181]
	v_pk_fma_f32 v[68:69], v[68:69], v[176:177], v[216:217]
	v_pk_fma_f32 v[72:73], v[72:73], v[176:177], v[218:219] neg_lo:[0,0,1] neg_hi:[0,0,1]
	v_cvt_pk_bf16_f32 v70, v70, v71
	v_cvt_pk_bf16_f32 v71, v72, v73
	v_cvt_pk_bf16_f32 v72, v66, v67
	v_cvt_pk_bf16_f32 v73, v68, v69
	s_nop 1
	v_permlane16_swap_b32_e32 v70, v72
	v_permlane16_swap_b32_e32 v71, v73
	global_store_dwordx4 v214, v[70:73], s[42:43] offset:256
	s_add_u32 s42, s42, s11
	s_addc_u32 s43, s43, 0
	s_waitcnt vmcnt(14)
	v_pk_mul_f32 v[218:219], v[58:59], v[186:187]
	v_pk_mul_f32 v[216:217], v[62:63], v[186:187]
	v_pk_fma_f32 v[58:59], v[58:59], v[182:183], v[216:217]
	v_pk_fma_f32 v[62:63], v[62:63], v[182:183], v[218:219] neg_lo:[0,0,1] neg_hi:[0,0,1]
	v_pk_mul_f32 v[218:219], v[60:61], v[188:189]
	v_pk_mul_f32 v[216:217], v[64:65], v[188:189]
	v_pk_fma_f32 v[60:61], v[60:61], v[184:185], v[216:217]
	v_pk_fma_f32 v[64:65], v[64:65], v[184:185], v[218:219] neg_lo:[0,0,1] neg_hi:[0,0,1]
	v_cvt_pk_bf16_f32 v62, v62, v63
	v_cvt_pk_bf16_f32 v63, v64, v65
	v_cvt_pk_bf16_f32 v64, v58, v59
	v_cvt_pk_bf16_f32 v65, v60, v61
	s_nop 1
	v_permlane16_swap_b32_e32 v62, v64
	v_permlane16_swap_b32_e32 v63, v65
	global_store_dwordx4 v214, v[62:65], s[42:43]
	v_pk_mul_f32 v[218:219], v[50:51], v[186:187]
	v_pk_mul_f32 v[216:217], v[54:55], v[186:187]
	v_pk_fma_f32 v[50:51], v[50:51], v[182:183], v[216:217]
	v_pk_fma_f32 v[54:55], v[54:55], v[182:183], v[218:219] neg_lo:[0,0,1] neg_hi:[0,0,1]
	v_pk_mul_f32 v[218:219], v[52:53], v[188:189]
	v_pk_mul_f32 v[216:217], v[56:57], v[188:189]
	v_pk_fma_f32 v[52:53], v[52:53], v[184:185], v[216:217]
	v_pk_fma_f32 v[56:57], v[56:57], v[184:185], v[218:219] neg_lo:[0,0,1] neg_hi:[0,0,1]
	v_cvt_pk_bf16_f32 v54, v54, v55
	v_cvt_pk_bf16_f32 v55, v56, v57
	v_cvt_pk_bf16_f32 v56, v50, v51
	v_cvt_pk_bf16_f32 v57, v52, v53
	s_nop 1
	v_permlane16_swap_b32_e32 v54, v56
	v_permlane16_swap_b32_e32 v55, v57
	global_store_dwordx4 v214, v[54:57], s[42:43] offset:256
	s_add_u32 s42, s42, s10
	s_addc_u32 s43, s43, 0
	s_waitcnt vmcnt(14)
; __device__ __forceinline__ unsigned pk_bf16(float lo, float hi) { const f32x2 v = {lo, hi}; const bf16v2 b = __builtin_convertvector(v, bf16v2); return __builtin_bit_cast(unsigned, b); }
; template <class Epi>
; __device__ __forceinline__ void gemm_phase(const bf16_t* __restrict__ A, const bf16_t* __restrict__ Bt, int M, int N, LAS unsigned char* lds, const Epi& epi, int vcu) {
;     ...
;         for (int ai = 0; ai < 2; ++ai)
; #pragma unroll
;             for (int mp = 0; mp < 2; ++mp) {
; #pragma unroll
;                 for (int mq = 0; mq < 2; ++mq)
; #pragma unroll
;                     for (int bj = 0; bj < 2; ++bj) { const int m = mp * 2 + mq;
;                         epi(brow + ai * HALF + wr * 64 + m * 16 + fre, (bcol + bj * HALF + wc * 32) >> 5, fqe, acc[ai][bj][m][0], acc[ai][bj][m][1]); }
;     __device__ __forceinline__ void operator()(int row, int G, int fq, f32x4 v0, f32x4 v1) const {
;         const int col32 = G * 32;
;         const unsigned ro = (unsigned)row * (unsigned)ld;
;         if (col32 < rope_end) {
;             const int half = hd >> 1, hb = col32 & ~(hd - 1), d0 = ((col32 & (hd - 1)) >> 5) * 16 + fq * 4, pos = row & (SEQ - 1);
;             const unsigned to = (unsigned)(pos * half + d0);
;             const f32x4 c = *(const f32x4*)(cosT + to), s = *(const f32x4*)(sinT + to);
;             const f32x4 o1 = v0 * c - v1 * s, o2 = v1 * c + v0 * s;
;             u32x2 w1, w2; w1.x = pk_bf16(o1[0], o1[1]); w1.y = pk_bf16(o1[2], o1[3]); w2.x = pk_bf16(o2[0], o2[1]); w2.y = pk_bf16(o2[2], o2[3]);
;             *(u32x2*)(out + (ro + (unsigned)(hb + d0))) = w1; *(u32x2*)(out + (ro + (unsigned)(hb + half + d0))) = w2;
	v_pk_mul_f32 v[218:219], v[42:43], v[194:195]
	v_pk_mul_f32 v[216:217], v[46:47], v[194:195]
	v_pk_fma_f32 v[42:43], v[42:43], v[190:191], v[216:217]
	v_pk_fma_f32 v[46:47], v[46:47], v[190:191], v[218:219] neg_lo:[0,0,1] neg_hi:[0,0,1]
	v_pk_mul_f32 v[218:219], v[44:45], v[196:197]
	v_pk_mul_f32 v[216:217], v[48:49], v[196:197]
	v_pk_fma_f32 v[44:45], v[44:45], v[192:193], v[216:217]
	v_pk_fma_f32 v[48:49], v[48:49], v[192:193], v[218:219] neg_lo:[0,0,1] neg_hi:[0,0,1]
	v_cvt_pk_bf16_f32 v46, v46, v47
	v_cvt_pk_bf16_f32 v47, v48, v49
	v_cvt_pk_bf16_f32 v48, v42, v43
	v_cvt_pk_bf16_f32 v49, v44, v45
	s_nop 1
	v_permlane16_swap_b32_e32 v46, v48
	v_permlane16_swap_b32_e32 v47, v49
	global_store_dwordx4 v214, v[46:49], s[42:43]
	v_pk_mul_f32 v[218:219], v[34:35], v[194:195]
	v_pk_mul_f32 v[216:217], v[38:39], v[194:195]
	v_pk_fma_f32 v[34:35], v[34:35], v[190:191], v[216:217]
	v_pk_fma_f32 v[38:39], v[38:39], v[190:191], v[218:219] neg_lo:[0,0,1] neg_hi:[0,0,1]
	v_pk_mul_f32 v[218:219], v[36:37], v[196:197]
	v_pk_mul_f32 v[216:217], v[40:41], v[196:197]
	v_pk_fma_f32 v[36:37], v[36:37], v[192:193], v[216:217]
	v_pk_fma_f32 v[40:41], v[40:41], v[192:193], v[218:219] neg_lo:[0,0,1] neg_hi:[0,0,1]
	v_cvt_pk_bf16_f32 v38, v38, v39
	v_cvt_pk_bf16_f32 v39, v40, v41
	v_cvt_pk_bf16_f32 v40, v34, v35
	v_cvt_pk_bf16_f32 v41, v36, v37
	s_nop 1
	v_permlane16_swap_b32_e32 v38, v40
	v_permlane16_swap_b32_e32 v39, v41
	global_store_dwordx4 v214, v[38:41], s[42:43] offset:256
	s_add_u32 s42, s42, s10
	s_addc_u32 s43, s43, 0
	s_waitcnt vmcnt(10)
	v_pk_mul_f32 v[218:219], v[26:27], v[154:155]
	v_pk_mul_f32 v[216:217], v[30:31], v[154:155]
	v_pk_fma_f32 v[26:27], v[26:27], v[150:151], v[216:217]
	v_pk_fma_f32 v[30:31], v[30:31], v[150:151], v[218:219] neg_lo:[0,0,1] neg_hi:[0,0,1]
	v_pk_mul_f32 v[218:219], v[28:29], v[156:157]
	v_pk_mul_f32 v[216:217], v[32:33], v[156:157]
	v_pk_fma_f32 v[28:29], v[28:29], v[152:153], v[216:217]
	v_pk_fma_f32 v[32:33], v[32:33], v[152:153], v[218:219] neg_lo:[0,0,1] neg_hi:[0,0,1]
	v_cvt_pk_bf16_f32 v30, v30, v31
	v_cvt_pk_bf16_f32 v31, v32, v33
	v_cvt_pk_bf16_f32 v32, v26, v27
	v_cvt_pk_bf16_f32 v33, v28, v29
	s_nop 1
	v_permlane16_swap_b32_e32 v30, v32
	v_permlane16_swap_b32_e32 v31, v33
	global_store_dwordx4 v214, v[30:33], s[42:43]
	v_pk_mul_f32 v[218:219], v[18:19], v[154:155]
	v_pk_mul_f32 v[216:217], v[22:23], v[154:155]
	v_pk_fma_f32 v[18:19], v[18:19], v[150:151], v[216:217]
	v_pk_fma_f32 v[22:23], v[22:23], v[150:151], v[218:219] neg_lo:[0,0,1] neg_hi:[0,0,1]
	v_pk_mul_f32 v[218:219], v[20:21], v[156:157]
	v_pk_mul_f32 v[216:217], v[24:25], v[156:157]
	v_pk_fma_f32 v[20:21], v[20:21], v[152:153], v[216:217]
	v_pk_fma_f32 v[24:25], v[24:25], v[152:153], v[218:219] neg_lo:[0,0,1] neg_hi:[0,0,1]
	v_cvt_pk_bf16_f32 v22, v22, v23
	v_cvt_pk_bf16_f32 v23, v24, v25
	v_cvt_pk_bf16_f32 v24, v18, v19
	v_cvt_pk_bf16_f32 v25, v20, v21
	s_nop 1
	v_permlane16_swap_b32_e32 v22, v24
	v_permlane16_swap_b32_e32 v23, v25
	global_store_dwordx4 v214, v[22:25], s[42:43] offset:256
	s_add_u32 s42, s42, s10
	s_addc_u32 s43, s43, 0
	s_waitcnt vmcnt(10)
	v_pk_mul_f32 v[218:219], v[10:11], v[162:163]
	v_pk_mul_f32 v[216:217], v[14:15], v[162:163]
	v_pk_fma_f32 v[10:11], v[10:11], v[158:159], v[216:217]
	v_pk_fma_f32 v[14:15], v[14:15], v[158:159], v[218:219] neg_lo:[0,0,1] neg_hi:[0,0,1]
	v_pk_mul_f32 v[218:219], v[12:13], v[164:165]
	v_pk_mul_f32 v[216:217], v[16:17], v[164:165]
	v_pk_fma_f32 v[12:13], v[12:13], v[160:161], v[216:217]
	v_pk_fma_f32 v[16:17], v[16:17], v[160:161], v[218:219] neg_lo:[0,0,1] neg_hi:[0,0,1]
	v_cvt_pk_bf16_f32 v14, v14, v15
	v_cvt_pk_bf16_f32 v15, v16, v17
	v_cvt_pk_bf16_f32 v16, v10, v11
	v_cvt_pk_bf16_f32 v17, v12, v13
	s_nop 1
	v_permlane16_swap_b32_e32 v14, v16
	v_permlane16_swap_b32_e32 v15, v17
	global_store_dwordx4 v214, v[14:17], s[42:43]
	v_pk_mul_f32 v[218:219], v[2:3], v[162:163]
	v_pk_mul_f32 v[216:217], v[6:7], v[162:163]
	v_pk_fma_f32 v[2:3], v[2:3], v[158:159], v[216:217]
	v_pk_fma_f32 v[6:7], v[6:7], v[158:159], v[218:219] neg_lo:[0,0,1] neg_hi:[0,0,1]
	v_pk_mul_f32 v[218:219], v[4:5], v[164:165]
	v_pk_mul_f32 v[216:217], v[8:9], v[164:165]
	v_pk_fma_f32 v[4:5], v[4:5], v[160:161], v[216:217]
	v_pk_fma_f32 v[8:9], v[8:9], v[160:161], v[218:219] neg_lo:[0,0,1] neg_hi:[0,0,1]
	v_cvt_pk_bf16_f32 v6, v6, v7
	v_cvt_pk_bf16_f32 v7, v8, v9
	v_cvt_pk_bf16_f32 v8, v2, v3
	v_cvt_pk_bf16_f32 v9, v4, v5
	s_nop 1
	v_permlane16_swap_b32_e32 v6, v8
	v_permlane16_swap_b32_e32 v7, v9
	global_store_dwordx4 v214, v[6:9], s[42:43] offset:256
	s_mov_b32 s83, s12
	s_mov_b32 s70, s13
	s_mov_b32 s36, s86
	s_mov_b32 s86, s87
	s_mov_b32 s87, s92
	s_mov_b64 s[12:13], s[72:73]
	s_mov_b32 s73, s93
	s_movk_i32 s72, 0x1fff
	s_branch .LBB0_251
